# FF1 K-loop: last two LDS-DMA pieces of each load phase issued inside the following MFMA phase (after MFMA 4 and 12)
# baseline (speedup 1.0000x reference)
.LBB0_211:
	s_add_i32 s73, s58, 2
	s_add_u32 s74, s56, 0x80
	s_addc_u32 s59, s57, 0
	s_add_i32 s78, 0, 0x10000
	s_cmp_eq_u32 s63, s58
	s_cselect_b32 s59, s51, s59
	s_cselect_b32 s58, s55, s74
	v_add_u32_e32 v0, s78, v146
	s_cselect_b32 s75, s45, s72
	s_cselect_b32 s74, s44, s67
	s_add_i32 s80, 0, 0x14000
	ds_read_b128 v[148:151], v0
	ds_read_b128 v[152:155], v0 offset:1024
	ds_read_b128 v[156:159], v0 offset:2048
	ds_read_b128 v[160:163], v0 offset:3072
	v_add_u32_e32 v0, s80, v146
	ds_read_b128 v[164:167], v0
	ds_read_b128 v[168:171], v0 offset:1024
	ds_read_b128 v[172:175], v0 offset:2048
	ds_read_b128 v[176:179], v0 offset:3072
	v_lshl_add_u64 v[142:143], s[56:57], 0, v[136:137]
	s_mov_b32 m0, s31
	global_load_lds_dwordx4 v[142:143], off
	v_lshl_add_u64 v[142:143], s[56:57], 0, v[132:133]
	s_mov_b32 m0, s53
	s_nop 0
	global_load_lds_dwordx4 v[142:143], off
	v_lshl_add_u64 v[238:239], s[56:57], 0, v[138:139]
	v_lshl_add_u64 v[240:241], s[56:57], 0, v[140:141]
	ds_read_b128 v[180:183], v147
	ds_read_b128 v[184:187], v147 offset:1024
	ds_read_b128 v[200:203], v147 offset:2048
	ds_read_b128 v[204:207], v147 offset:3072
	ds_read_b128 v[208:211], v147 offset:4096
	ds_read_b128 v[212:215], v147 offset:5120
	ds_read_b128 v[216:219], v147 offset:6144
	ds_read_b128 v[220:223], v147 offset:7168
	s_waitcnt vmcnt(6)
	s_waitcnt lgkmcnt(0)
	s_barrier
	s_setprio 1
	s_waitcnt lgkmcnt(0)
	v_mfma_f32_16x16x32_bf16 v[122:125], v[148:151], v[180:183], v[122:125]
	v_mfma_f32_16x16x32_bf16 v[126:129], v[156:159], v[180:183], v[126:129]
	v_mfma_f32_16x16x32_bf16 v[110:113], v[148:151], v[200:203], v[110:113]
	s_add_i32 m0, s27, 0xc000
	v_mfma_f32_16x16x32_bf16 v[106:109], v[156:159], v[200:203], v[106:109]
	global_load_lds_dwordx4 v[238:239], off
	v_mfma_f32_16x16x32_bf16 v[94:97], v[148:151], v[208:211], v[94:97]
	v_mfma_f32_16x16x32_bf16 v[90:93], v[156:159], v[208:211], v[90:93]
	v_mfma_f32_16x16x32_bf16 v[78:81], v[148:151], v[216:219], v[78:81]
	v_mfma_f32_16x16x32_bf16 v[74:77], v[156:159], v[216:219], v[74:77]
	v_mfma_f32_16x16x32_bf16 v[122:125], v[152:155], v[184:187], v[122:125]
	v_mfma_f32_16x16x32_bf16 v[126:129], v[160:163], v[184:187], v[126:129]
	v_mfma_f32_16x16x32_bf16 v[110:113], v[152:155], v[204:207], v[110:113]
	s_add_i32 m0, s27, 0xe000
	v_mfma_f32_16x16x32_bf16 v[106:109], v[160:163], v[204:207], v[106:109]
	global_load_lds_dwordx4 v[240:241], off
	v_mfma_f32_16x16x32_bf16 v[94:97], v[152:155], v[212:215], v[94:97]
	v_mfma_f32_16x16x32_bf16 v[90:93], v[160:163], v[212:215], v[90:93]
	v_mfma_f32_16x16x32_bf16 v[78:81], v[152:155], v[220:223], v[78:81]
	v_mfma_f32_16x16x32_bf16 v[74:77], v[160:163], v[220:223], v[74:77]
	s_setprio 0
	s_setprio 1
	v_mfma_f32_16x16x32_bf16 v[118:121], v[164:167], v[180:183], v[118:121]
	v_mfma_f32_16x16x32_bf16 v[114:117], v[172:175], v[180:183], v[114:117]
	v_mfma_f32_16x16x32_bf16 v[102:105], v[164:167], v[200:203], v[102:105]
	v_mfma_f32_16x16x32_bf16 v[98:101], v[172:175], v[200:203], v[98:101]
	v_mfma_f32_16x16x32_bf16 v[86:89], v[164:167], v[208:211], v[86:89]
	v_mfma_f32_16x16x32_bf16 v[82:85], v[172:175], v[208:211], v[82:85]
	v_mfma_f32_16x16x32_bf16 v[70:73], v[164:167], v[216:219], v[70:73]
	v_mfma_f32_16x16x32_bf16 v[66:69], v[172:175], v[216:219], v[66:69]
	v_mfma_f32_16x16x32_bf16 v[118:121], v[168:171], v[184:187], v[118:121]
	v_mfma_f32_16x16x32_bf16 v[114:117], v[176:179], v[184:187], v[114:117]
	v_mfma_f32_16x16x32_bf16 v[102:105], v[168:171], v[204:207], v[102:105]
	v_mfma_f32_16x16x32_bf16 v[98:101], v[176:179], v[204:207], v[98:101]
	v_mfma_f32_16x16x32_bf16 v[86:89], v[168:171], v[212:215], v[86:89]
	v_mfma_f32_16x16x32_bf16 v[82:85], v[176:179], v[212:215], v[82:85]
	v_mfma_f32_16x16x32_bf16 v[70:73], v[168:171], v[220:223], v[70:73]
	v_mfma_f32_16x16x32_bf16 v[66:69], v[176:179], v[220:223], v[66:69]
	s_setprio 0
	s_barrier
	s_add_i32 s78, s78, s5
	v_lshl_add_u64 v[142:143], s[74:75], 0, v[134:135]
	s_mov_b32 m0, s78
	ds_read_b128 v[180:183], v147 offset:16384
	ds_read_b128 v[184:187], v147 offset:17408
	ds_read_b128 v[200:203], v147 offset:18432
	ds_read_b128 v[204:207], v147 offset:19456
	ds_read_b128 v[208:211], v147 offset:20480
	ds_read_b128 v[212:215], v147 offset:21504
	ds_read_b128 v[216:219], v147 offset:22528
	ds_read_b128 v[220:223], v147 offset:23552
	global_load_lds_dwordx4 v[142:143], off
	s_add_i32 m0, s78, 0x2000
	v_lshl_add_u64 v[188:189], s[74:75], 0, v[130:131]
	s_add_u32 s74, s74, s6
	s_addc_u32 s75, s75, s7
	s_add_i32 s78, s80, s5
	global_load_lds_dwordx4 v[188:189], off
	v_lshl_add_u64 v[224:225], s[74:75], 0, v[134:135]
	v_lshl_add_u64 v[226:227], s[74:75], 0, v[130:131]
	v_lshl_add_u64 v[228:229], s[58:59], 0, v[136:137]
	v_lshl_add_u64 v[230:231], s[58:59], 0, v[132:133]
	s_waitcnt vmcnt(4)
	s_waitcnt lgkmcnt(0)
	s_barrier
	s_setprio 1
	s_waitcnt lgkmcnt(0)
	v_mfma_f32_16x16x32_bf16 v[62:65], v[148:151], v[180:183], v[62:65]
	v_mfma_f32_16x16x32_bf16 v[58:61], v[156:159], v[180:183], v[58:61]
	v_mfma_f32_16x16x32_bf16 v[46:49], v[148:151], v[200:203], v[46:49]
	s_mov_b32 m0, s78
	v_mfma_f32_16x16x32_bf16 v[42:45], v[156:159], v[200:203], v[42:45]
	global_load_lds_dwordx4 v[224:225], off
	v_mfma_f32_16x16x32_bf16 v[30:33], v[148:151], v[208:211], v[30:33]
	v_mfma_f32_16x16x32_bf16 v[26:29], v[156:159], v[208:211], v[26:29]
	v_mfma_f32_16x16x32_bf16 v[14:17], v[148:151], v[216:219], v[14:17]
	v_mfma_f32_16x16x32_bf16 v[10:13], v[156:159], v[216:219], v[10:13]
	v_mfma_f32_16x16x32_bf16 v[62:65], v[152:155], v[184:187], v[62:65]
	v_mfma_f32_16x16x32_bf16 v[58:61], v[160:163], v[184:187], v[58:61]
	v_mfma_f32_16x16x32_bf16 v[46:49], v[152:155], v[204:207], v[46:49]
	s_add_i32 m0, s78, 0x2000
	v_mfma_f32_16x16x32_bf16 v[42:45], v[160:163], v[204:207], v[42:45]
	global_load_lds_dwordx4 v[226:227], off
	v_mfma_f32_16x16x32_bf16 v[30:33], v[152:155], v[212:215], v[30:33]
	v_mfma_f32_16x16x32_bf16 v[26:29], v[160:163], v[212:215], v[26:29]
	v_mfma_f32_16x16x32_bf16 v[14:17], v[152:155], v[220:223], v[14:17]
	v_mfma_f32_16x16x32_bf16 v[10:13], v[160:163], v[220:223], v[10:13]
	s_setprio 0
	s_setprio 1
	v_mfma_f32_16x16x32_bf16 v[54:57], v[164:167], v[180:183], v[54:57]
	v_mfma_f32_16x16x32_bf16 v[50:53], v[172:175], v[180:183], v[50:53]
	v_mfma_f32_16x16x32_bf16 v[38:41], v[164:167], v[200:203], v[38:41]
	v_mfma_f32_16x16x32_bf16 v[34:37], v[172:175], v[200:203], v[34:37]
	v_mfma_f32_16x16x32_bf16 v[22:25], v[164:167], v[208:211], v[22:25]
	v_mfma_f32_16x16x32_bf16 v[18:21], v[172:175], v[208:211], v[18:21]
	v_mfma_f32_16x16x32_bf16 v[6:9], v[164:167], v[216:219], v[6:9]
	v_mfma_f32_16x16x32_bf16 v[2:5], v[172:175], v[216:219], v[2:5]
	v_mfma_f32_16x16x32_bf16 v[54:57], v[168:171], v[184:187], v[54:57]
	v_mfma_f32_16x16x32_bf16 v[50:53], v[176:179], v[184:187], v[50:53]
	v_mfma_f32_16x16x32_bf16 v[38:41], v[168:171], v[204:207], v[38:41]
	v_mfma_f32_16x16x32_bf16 v[34:37], v[176:179], v[204:207], v[34:37]
	v_mfma_f32_16x16x32_bf16 v[22:25], v[168:171], v[212:215], v[22:25]
	v_mfma_f32_16x16x32_bf16 v[18:21], v[176:179], v[212:215], v[18:21]
	v_mfma_f32_16x16x32_bf16 v[6:9], v[168:171], v[220:223], v[6:9]
	v_mfma_f32_16x16x32_bf16 v[2:5], v[176:179], v[220:223], v[2:5]
	s_setprio 0
	s_barrier
	s_add_i32 s74, 0, 0x18000
	v_add_u32_e32 v0, s74, v146
	s_add_i32 s75, 0, 0x1c000
	ds_read_b128 v[148:151], v0
	ds_read_b128 v[152:155], v0 offset:1024
	ds_read_b128 v[156:159], v0 offset:2048
	ds_read_b128 v[160:163], v0 offset:3072
	v_add_u32_e32 v0, s75, v146
	ds_read_b128 v[164:167], v0
	ds_read_b128 v[168:171], v0 offset:1024
	ds_read_b128 v[172:175], v0 offset:2048
	ds_read_b128 v[176:179], v0 offset:3072
	s_add_u32 s58, s58, s2
	s_addc_u32 s59, s59, s3
	s_mov_b32 m0, s27
	v_lshl_add_u64 v[232:233], s[58:59], 0, v[136:137]
	s_nop 0
	global_load_lds_dwordx4 v[228:229], off
	s_mov_b32 m0, s28
	s_nop 0
	global_load_lds_dwordx4 v[230:231], off
	v_lshl_add_u64 v[242:243], s[58:59], 0, v[132:133]
	ds_read_b128 v[180:183], v147 offset:32768
	ds_read_b128 v[184:187], v147 offset:33792
	ds_read_b128 v[200:203], v147 offset:34816
	ds_read_b128 v[204:207], v147 offset:35840
	ds_read_b128 v[208:211], v147 offset:36864
	ds_read_b128 v[212:215], v147 offset:37888
	ds_read_b128 v[216:219], v147 offset:38912
	ds_read_b128 v[220:223], v147 offset:39936
	s_waitcnt vmcnt(6)
	s_waitcnt lgkmcnt(0)
	s_barrier
	s_setprio 1
	s_waitcnt lgkmcnt(0)
	v_mfma_f32_16x16x32_bf16 v[122:125], v[148:151], v[180:183], v[122:125]
	v_mfma_f32_16x16x32_bf16 v[126:129], v[156:159], v[180:183], v[126:129]
	v_mfma_f32_16x16x32_bf16 v[110:113], v[148:151], v[200:203], v[110:113]
	s_mov_b32 m0, s29
	v_mfma_f32_16x16x32_bf16 v[106:109], v[156:159], v[200:203], v[106:109]
	global_load_lds_dwordx4 v[232:233], off
	v_mfma_f32_16x16x32_bf16 v[94:97], v[148:151], v[208:211], v[94:97]
	v_mfma_f32_16x16x32_bf16 v[90:93], v[156:159], v[208:211], v[90:93]
	v_mfma_f32_16x16x32_bf16 v[78:81], v[148:151], v[216:219], v[78:81]
	v_mfma_f32_16x16x32_bf16 v[74:77], v[156:159], v[216:219], v[74:77]
	v_mfma_f32_16x16x32_bf16 v[122:125], v[152:155], v[184:187], v[122:125]
	v_mfma_f32_16x16x32_bf16 v[126:129], v[160:163], v[184:187], v[126:129]
	v_mfma_f32_16x16x32_bf16 v[110:113], v[152:155], v[204:207], v[110:113]
	s_mov_b32 m0, s30
	v_mfma_f32_16x16x32_bf16 v[106:109], v[160:163], v[204:207], v[106:109]
	global_load_lds_dwordx4 v[242:243], off
	v_mfma_f32_16x16x32_bf16 v[94:97], v[152:155], v[212:215], v[94:97]
	v_mfma_f32_16x16x32_bf16 v[90:93], v[160:163], v[212:215], v[90:93]
	v_mfma_f32_16x16x32_bf16 v[78:81], v[152:155], v[220:223], v[78:81]
	v_mfma_f32_16x16x32_bf16 v[74:77], v[160:163], v[220:223], v[74:77]
	s_setprio 0
	s_setprio 1
	v_mfma_f32_16x16x32_bf16 v[118:121], v[164:167], v[180:183], v[118:121]
	v_mfma_f32_16x16x32_bf16 v[114:117], v[172:175], v[180:183], v[114:117]
	v_mfma_f32_16x16x32_bf16 v[102:105], v[164:167], v[200:203], v[102:105]
	v_mfma_f32_16x16x32_bf16 v[98:101], v[172:175], v[200:203], v[98:101]
	v_mfma_f32_16x16x32_bf16 v[86:89], v[164:167], v[208:211], v[86:89]
	v_mfma_f32_16x16x32_bf16 v[82:85], v[172:175], v[208:211], v[82:85]
	v_mfma_f32_16x16x32_bf16 v[70:73], v[164:167], v[216:219], v[70:73]
	v_mfma_f32_16x16x32_bf16 v[66:69], v[172:175], v[216:219], v[66:69]
	v_mfma_f32_16x16x32_bf16 v[118:121], v[168:171], v[184:187], v[118:121]
	v_mfma_f32_16x16x32_bf16 v[114:117], v[176:179], v[184:187], v[114:117]
	v_mfma_f32_16x16x32_bf16 v[102:105], v[168:171], v[204:207], v[102:105]
	v_mfma_f32_16x16x32_bf16 v[98:101], v[176:179], v[204:207], v[98:101]
	v_mfma_f32_16x16x32_bf16 v[86:89], v[168:171], v[212:215], v[86:89]
	v_mfma_f32_16x16x32_bf16 v[82:85], v[176:179], v[212:215], v[82:85]
	v_mfma_f32_16x16x32_bf16 v[70:73], v[168:171], v[220:223], v[70:73]
	v_mfma_f32_16x16x32_bf16 v[66:69], v[176:179], v[220:223], v[66:69]
	s_setprio 0
	s_barrier
	s_add_i32 s58, s74, s5
	v_lshl_add_u64 v[142:143], v[142:143], 0, s[24:25]
	s_mov_b32 m0, s58
	ds_read_b128 v[180:183], v147 offset:49152
	ds_read_b128 v[184:187], v147 offset:50176
	ds_read_b128 v[200:203], v147 offset:51200
	ds_read_b128 v[204:207], v147 offset:52224
	ds_read_b128 v[208:211], v147 offset:53248
	ds_read_b128 v[212:215], v147 offset:54272
	ds_read_b128 v[216:219], v147 offset:55296
	ds_read_b128 v[220:223], v147 offset:56320
	global_load_lds_dwordx4 v[142:143], off
	v_lshl_add_u64 v[142:143], v[188:189], 0, s[24:25]
	s_add_i32 m0, s58, 0x2000
	s_add_i32 s58, s75, s5
	global_load_lds_dwordx4 v[142:143], off
	v_lshl_add_u64 v[244:245], v[224:225], 0, s[24:25]
	v_lshl_add_u64 v[246:247], v[226:227], 0, s[24:25]
	s_waitcnt vmcnt(4)
	s_waitcnt lgkmcnt(0)
	s_barrier
	s_setprio 1
	s_waitcnt lgkmcnt(0)
	v_mfma_f32_16x16x32_bf16 v[62:65], v[148:151], v[180:183], v[62:65]
	v_mfma_f32_16x16x32_bf16 v[58:61], v[156:159], v[180:183], v[58:61]
	v_mfma_f32_16x16x32_bf16 v[46:49], v[148:151], v[200:203], v[46:49]
	s_mov_b32 m0, s58
	v_mfma_f32_16x16x32_bf16 v[42:45], v[156:159], v[200:203], v[42:45]
	global_load_lds_dwordx4 v[244:245], off
	v_mfma_f32_16x16x32_bf16 v[30:33], v[148:151], v[208:211], v[30:33]
	v_mfma_f32_16x16x32_bf16 v[26:29], v[156:159], v[208:211], v[26:29]
	v_mfma_f32_16x16x32_bf16 v[14:17], v[148:151], v[216:219], v[14:17]
	v_mfma_f32_16x16x32_bf16 v[10:13], v[156:159], v[216:219], v[10:13]
	v_mfma_f32_16x16x32_bf16 v[62:65], v[152:155], v[184:187], v[62:65]
	v_mfma_f32_16x16x32_bf16 v[58:61], v[160:163], v[184:187], v[58:61]
	v_mfma_f32_16x16x32_bf16 v[46:49], v[152:155], v[204:207], v[46:49]
	s_add_i32 m0, s58, 0x2000
	v_mfma_f32_16x16x32_bf16 v[42:45], v[160:163], v[204:207], v[42:45]
	global_load_lds_dwordx4 v[246:247], off
	v_mfma_f32_16x16x32_bf16 v[30:33], v[152:155], v[212:215], v[30:33]
	v_mfma_f32_16x16x32_bf16 v[26:29], v[160:163], v[212:215], v[26:29]
	v_mfma_f32_16x16x32_bf16 v[14:17], v[152:155], v[220:223], v[14:17]
	v_mfma_f32_16x16x32_bf16 v[10:13], v[160:163], v[220:223], v[10:13]
	s_setprio 0
	s_setprio 1
	v_mfma_f32_16x16x32_bf16 v[54:57], v[164:167], v[180:183], v[54:57]
	v_mfma_f32_16x16x32_bf16 v[50:53], v[172:175], v[180:183], v[50:53]
	v_mfma_f32_16x16x32_bf16 v[38:41], v[164:167], v[200:203], v[38:41]
	v_mfma_f32_16x16x32_bf16 v[34:37], v[172:175], v[200:203], v[34:37]
	v_mfma_f32_16x16x32_bf16 v[22:25], v[164:167], v[208:211], v[22:25]
	v_mfma_f32_16x16x32_bf16 v[18:21], v[172:175], v[208:211], v[18:21]
	v_mfma_f32_16x16x32_bf16 v[6:9], v[164:167], v[216:219], v[6:9]
	v_mfma_f32_16x16x32_bf16 v[2:5], v[172:175], v[216:219], v[2:5]
	v_mfma_f32_16x16x32_bf16 v[54:57], v[168:171], v[184:187], v[54:57]
	v_mfma_f32_16x16x32_bf16 v[50:53], v[176:179], v[184:187], v[50:53]
	v_mfma_f32_16x16x32_bf16 v[38:41], v[168:171], v[204:207], v[38:41]
	v_mfma_f32_16x16x32_bf16 v[34:37], v[176:179], v[204:207], v[34:37]
	v_mfma_f32_16x16x32_bf16 v[22:25], v[168:171], v[212:215], v[22:25]
	v_mfma_f32_16x16x32_bf16 v[18:21], v[176:179], v[212:215], v[18:21]
	v_mfma_f32_16x16x32_bf16 v[6:9], v[168:171], v[220:223], v[6:9]
	v_mfma_f32_16x16x32_bf16 v[2:5], v[176:179], v[220:223], v[2:5]
	s_setprio 0
	s_barrier
	s_add_u32 s56, s56, 0x100
	s_addc_u32 s57, s57, 0
	s_add_u32 s67, s67, 0x100
	s_addc_u32 s72, s72, 0
	s_cmp_ge_i32 s73, s60
	s_mov_b32 s58, s73
	s_cbranch_scc0 .LBB0_211
	v_readlane_b32 s74, v236, 30
	v_readlane_b32 s75, v236, 31
	v_readlane_b32 s73, v236, 32
	s_mov_b32 s78, s76

	.amdhsa_kernel _Z10fwd_kernel4Args
		.amdhsa_group_segment_fixed_size 0
		.amdhsa_private_segment_fixed_size 0
		.amdhsa_kernarg_size 400
		.amdhsa_user_sgpr_count 2
		.amdhsa_user_sgpr_dispatch_ptr 0
		.amdhsa_user_sgpr_queue_ptr 0
		.amdhsa_user_sgpr_kernarg_segment_ptr 1
		.amdhsa_user_sgpr_dispatch_id 0
		.amdhsa_user_sgpr_kernarg_preload_length 0
		.amdhsa_user_sgpr_kernarg_preload_offset 0
		.amdhsa_user_sgpr_private_segment_size 0
		.amdhsa_uses_dynamic_stack 0
		.amdhsa_enable_private_segment 0
		.amdhsa_system_sgpr_workgroup_id_x 1
		.amdhsa_system_sgpr_workgroup_id_y 0
		.amdhsa_system_sgpr_workgroup_id_z 0
		.amdhsa_system_sgpr_workgroup_info 0
		.amdhsa_system_vgpr_workitem_id 2
		.amdhsa_next_free_vgpr 248
		.amdhsa_next_free_sgpr 98
		.amdhsa_accum_offset 248
		.amdhsa_reserve_vcc 1
		.amdhsa_float_round_mode_32 0
		.amdhsa_float_round_mode_16_64 0
		.amdhsa_float_denorm_mode_32 3
		.amdhsa_float_denorm_mode_16_64 3
		.amdhsa_dx10_clamp 1
		.amdhsa_ieee_mode 1
		.amdhsa_fp16_overflow 0
		.amdhsa_tg_split 0
		.amdhsa_exception_fp_ieee_invalid_op 0
		.amdhsa_exception_fp_denorm_src 0
		.amdhsa_exception_fp_ieee_div_zero 0
		.amdhsa_exception_fp_ieee_overflow 0
		.amdhsa_exception_fp_ieee_underflow 0
		.amdhsa_exception_fp_ieee_inexact 0
		.amdhsa_exception_int_div_zero 0
	.end_amdhsa_kernel

amdhsa.kernels:
  - .agpr_count:     0
    .args:
      - .offset:         0
        .size:           144
        .value_kind:     by_value
      - .offset:         144
        .size:           4
        .value_kind:     hidden_block_count_x
      - .offset:         148
        .size:           4
        .value_kind:     hidden_block_count_y
      - .offset:         152
        .size:           4
        .value_kind:     hidden_block_count_z
      - .offset:         156
        .size:           2
        .value_kind:     hidden_group_size_x
      - .offset:         158
        .size:           2
        .value_kind:     hidden_group_size_y
      - .offset:         160
        .size:           2
        .value_kind:     hidden_group_size_z
      - .offset:         162
        .size:           2
        .value_kind:     hidden_remainder_x
      - .offset:         164
        .size:           2
        .value_kind:     hidden_remainder_y
      - .offset:         166
        .size:           2
        .value_kind:     hidden_remainder_z
      - .offset:         184
        .size:           8
        .value_kind:     hidden_global_offset_x
      - .offset:         192
        .size:           8
        .value_kind:     hidden_global_offset_y
      - .offset:         200
        .size:           8
        .value_kind:     hidden_global_offset_z
      - .offset:         208
        .size:           2
        .value_kind:     hidden_grid_dims
      - .offset:         232
        .size:           8
        .value_kind:     hidden_multigrid_sync_arg
      - .offset:         264
        .size:           4
        .value_kind:     hidden_dynamic_lds_size
    .group_segment_fixed_size: 0
    .kernarg_segment_align: 8
    .kernarg_segment_size: 400
    .language:       OpenCL C
    .language_version:
      - 2
      - 0
    .max_flat_workgroup_size: 512
    .name:           _Z10fwd_kernel4Args
    .private_segment_fixed_size: 0
    .sgpr_count:     104
    .sgpr_spill_count: 216
    .symbol:         _Z10fwd_kernel4Args.kd
    .uniform_work_group_size: 1
    .uses_dynamic_stack: false
    .vgpr_count:     248
    .vgpr_spill_count: 0
    .wavefront_size: 64
